# grid barrier restructure: per-XCD arrival count elects the L2 flusher, all workgroups poll one global flushed-XCD count (drops the XGEN relay level, divisions, census reload) at 9 of 12 barrier sites
# speedup vs baseline: 1.0092x; 1.0092x over previous
; #define LAS __attribute__((address_space(3)))
; #define FRESH() do { int _t = threadIdx.x; asm volatile("" : "+v"(_t)); C.tid = _t; C.lane = _t & 63; C.wave = __builtin_amdgcn_readfirstlane(_t >> 6); size_t _z = 0; asm volatile("" : "+s"(_z)); C.ws = prm.ws + _z; C.out = prm.out + _z; } while (0)
; __global__ void __launch_bounds__(NTHR, 2) fwd_megakernel(Params prm) {
;     extern __shared__ __attribute__((aligned(16))) unsigned char shm[];
;     cg::grid_group grid = cg::this_grid();
;     Ctx C;
;     C.P = &prm;
;     C.out = prm.out; C.ws = prm.ws; C.bid = blockIdx.x; C.G = gridDim.x; C.lds = shm;
;     ...
;     FRESH();
;     LAS unsigned char* ldsg = (LAS unsigned char*)shm;
;     volatile LAS unsigned* xst = (volatile LAS unsigned*)(ldsg + (LDS_BYTES - 16));
;     if (threadIdx.x == 0) { xst[0] = 0u; xst[1] = 0u; }
;     __syncthreads();
;     const XcdBarrier xbar = xcd_barrier_post((unsigned*)(prm.ws + OFF_BAR), xst);
_Z14fwd_megakernel6Params:
	s_load_dwordx4 s[24:27], s[0:1], 0x100
	s_load_dword s8, s[0:1], 0x110
	s_mov_b32 s90, s2
	s_add_u32 s2, s0, 0x108
	s_addc_u32 s3, s1, 0
	v_and_b32_e32 v224, 0x3ff, v0
	v_writelane_b32 v251, s2, 0
	v_mov_b32_e32 v1, v224
	s_mov_b64 s[4:5], 0
	v_writelane_b32 v255, s4, 50
	v_writelane_b32 v255, s4, 51
	v_writelane_b32 v251, s3, 1
	v_cmp_eq_u32_e64 s[6:7], 0, v224
	s_mov_b64 s[2:3], exec
	s_nop 0
	v_writelane_b32 v251, s6, 2
	s_nop 1
	v_writelane_b32 v251, s7, 3
	s_and_b64 s[6:7], s[2:3], s[6:7]
	s_mov_b64 exec, s[6:7]
	s_cbranch_execz .LBB0_2
	s_add_i32 s6, 0, 0x26ff0
	v_mov_b32_e32 v1, 0
	v_mov_b32_e32 v2, s6
	s_add_i32 s6, 0, 0x26ff4
	ds_write_b32 v2, v1
	v_mov_b32_e32 v2, s6
	ds_write_b32 v2, v1

; __device__ __forceinline__ unsigned xb_ld(unsigned* p)              { return __hip_atomic_load(p, __ATOMIC_RELAXED, __HIP_MEMORY_SCOPE_AGENT); }
; __device__ __forceinline__ unsigned xb_add(unsigned* p, unsigned v) { return __hip_atomic_fetch_add(p, v, __ATOMIC_RELAXED, __HIP_MEMORY_SCOPE_AGENT); }
; #define XB_SPIN(cond, bar) do { unsigned _sp = 0; while (cond) { __builtin_amdgcn_s_sleep(1); \
;     if ((++_sp & 255u) == 0u) { if (xb_ld(&(bar)[XB_TMO])) break; if (_sp > XB_SPIN_CAP) { atomicAdd(&(bar)[XB_TMO], 1u); break; } } } } while (0)
; __device__ __forceinline__ void xcd_barrier(const XcdBarrier& b) {
;     asm volatile("s_waitcnt vmcnt(0)" ::: "memory");
;     __syncthreads();
;     if (threadIdx.x == 0) {
;         unsigned* bar = b.bar;
;         __builtin_amdgcn_s_waitcnt(0);
;         unsigned nloc = b.st[0], nx = b.st[1];
;         if (nloc == 0u) { xcd_barrier_complete(bar, b.x, nloc, nx); b.st[0] = nloc; b.st[1] = nx; }
;         const unsigned old = xb_add(&bar[XB_XSUB(b.x)], 1u);
;         const unsigned gen = old / nloc;
;         if (old + 1u == (gen + 1u) * nloc) {
;             __builtin_amdgcn_fence(__ATOMIC_RELEASE, "agent");
;             asm volatile("s_waitcnt vmcnt(0)" ::: "memory");
;             const unsigned og = xb_add(&bar[XB_TOP], 1u);
;             const unsigned tg = og / nx;
;             if (og + 1u == (tg + 1u) * nx) xb_add(&bar[XB_TOPGEN], 1u);
;             else XB_SPIN(xb_ld(&bar[XB_TOPGEN]) == tg, bar);
;             __builtin_amdgcn_fence(__ATOMIC_ACQUIRE, "agent");
;             xb_add(&bar[XB_XGEN(b.x)], 1u);
;             asm volatile("s_waitcnt vmcnt(0)" ::: "memory");
;         } else {
;             XB_SPIN(xb_ld(&bar[XB_XGEN(b.x)]) == gen, bar);
;             __builtin_amdgcn_fence(__ATOMIC_ACQUIRE, "agent");
;             asm volatile("s_waitcnt vmcnt(0)" ::: "memory");
;         }
.LBB0_490:
	s_waitcnt vmcnt(0)
	s_barrier
	s_mov_b64 s[0:1], exec
	v_readlane_b32 s4, v251, 2
	v_readlane_b32 s5, v251, 3
	s_and_b64 s[4:5], s[0:1], s[4:5]
	s_mov_b64 exec, s[4:5]
	s_cbranch_execz .LBB0_542
	v_mov_b32_e32 v0, 0x26ff0
	ds_read_b64 v[2:3], v0
	s_getreg_b32 s4, hwreg(HW_REG_XCC_ID, 0, 4)
	v_readlane_b32 s6, v255, 50
	v_readlane_b32 s7, v255, 51
	s_lshl_b32 s4, s4, 6
	s_add_u32 s4, s4, 0x1eb03800
	s_add_u32 s8, s24, s4
	s_addc_u32 s9, s25, 0
	s_add_u32 s10, s24, 0x1eb03c00
	s_addc_u32 s11, s25, 0
	v_mov_b32_e32 v0, 1
	s_waitcnt vmcnt(0) lgkmcnt(0)
	global_atomic_add v1, v65, v0, s[8:9] sc0
	v_readfirstlane_b32 s4, v2
	v_readfirstlane_b32 s5, v3
	s_add_i32 s6, s6, s4
	s_add_i32 s7, s7, s5
	v_writelane_b32 v255, s6, 50
	v_writelane_b32 v255, s7, 51
	s_waitcnt vmcnt(0)
	v_add_u32_e32 v1, 1, v1
	v_cmp_eq_u32_e32 vcc, s6, v1
	s_cbranch_vccz .Lmy_gs_poll_3
	buffer_wbl2 sc1
	s_waitcnt vmcnt(0)
	global_atomic_add v65, v0, s[10:11]
.Lmy_gs_poll_3:
	global_load_dword v1, v65, s[10:11] sc1
	s_waitcnt vmcnt(0)
	v_cmp_gt_u32_e32 vcc, s7, v1
	s_cbranch_vccz .Lmy_gs_done_3
	s_sleep 2
	s_branch .Lmy_gs_poll_3
.Lmy_gs_done_3:
	buffer_inv sc1
	s_waitcnt vmcnt(0)

; __device__ __forceinline__ unsigned xb_ld(unsigned* p)              { return __hip_atomic_load(p, __ATOMIC_RELAXED, __HIP_MEMORY_SCOPE_AGENT); }
; __device__ __forceinline__ unsigned xb_add(unsigned* p, unsigned v) { return __hip_atomic_fetch_add(p, v, __ATOMIC_RELAXED, __HIP_MEMORY_SCOPE_AGENT); }
; #define XB_SPIN(cond, bar) do { unsigned _sp = 0; while (cond) { __builtin_amdgcn_s_sleep(1); \
;     if ((++_sp & 255u) == 0u) { if (xb_ld(&(bar)[XB_TMO])) break; if (_sp > XB_SPIN_CAP) { atomicAdd(&(bar)[XB_TMO], 1u); break; } } } } while (0)
; __device__ __forceinline__ void xcd_barrier(const XcdBarrier& b) {
;     asm volatile("s_waitcnt vmcnt(0)" ::: "memory");
;     __syncthreads();
;     if (threadIdx.x == 0) {
;         unsigned* bar = b.bar;
;         __builtin_amdgcn_s_waitcnt(0);
;         unsigned nloc = b.st[0], nx = b.st[1];
;         if (nloc == 0u) { xcd_barrier_complete(bar, b.x, nloc, nx); b.st[0] = nloc; b.st[1] = nx; }
;         const unsigned old = xb_add(&bar[XB_XSUB(b.x)], 1u);
;         const unsigned gen = old / nloc;
;         if (old + 1u == (gen + 1u) * nloc) {
;             __builtin_amdgcn_fence(__ATOMIC_RELEASE, "agent");
;             asm volatile("s_waitcnt vmcnt(0)" ::: "memory");
;             const unsigned og = xb_add(&bar[XB_TOP], 1u);
;             const unsigned tg = og / nx;
;             if (og + 1u == (tg + 1u) * nx) xb_add(&bar[XB_TOPGEN], 1u);
;             else XB_SPIN(xb_ld(&bar[XB_TOPGEN]) == tg, bar);
;             __builtin_amdgcn_fence(__ATOMIC_ACQUIRE, "agent");
;             xb_add(&bar[XB_XGEN(b.x)], 1u);
;             asm volatile("s_waitcnt vmcnt(0)" ::: "memory");
;         } else {
;             XB_SPIN(xb_ld(&bar[XB_XGEN(b.x)]) == gen, bar);
;             __builtin_amdgcn_fence(__ATOMIC_ACQUIRE, "agent");
;             asm volatile("s_waitcnt vmcnt(0)" ::: "memory");
;         }
.LBB0_550:
	v_readlane_b32 s0, v255, 11
	v_readlane_b32 s1, v255, 12
	s_or_b64 exec, exec, s[0:1]
	s_waitcnt vmcnt(0)
	s_barrier
	s_mov_b64 s[0:1], exec
	v_readlane_b32 s4, v251, 2
	v_readlane_b32 s5, v251, 3
	v_readlane_b32 s90, v254, 55
	v_readlane_b32 s96, v255, 3
	s_and_b64 s[4:5], s[0:1], s[4:5]
	v_readlane_b32 s91, v254, 56
	v_readlane_b32 s41, v254, 33
	s_movk_i32 s92, 0x1200
	s_mov_b32 s22, 0xc57ff000
	v_readlane_b32 s23, v254, 40
	v_readlane_b32 s30, v254, 41
	v_readlane_b32 s31, v254, 42
	v_readlane_b32 s40, v254, 43
	s_mov_b32 s66, 0x358637bd
	v_readlane_b32 s97, v255, 4
	v_readlane_b32 s50, v255, 9
	s_mov_b64 exec, s[4:5]
	s_cbranch_execz .LBB0_602
	v_mov_b32_e32 v0, 0x26ff0
	ds_read_b64 v[2:3], v0
	s_getreg_b32 s4, hwreg(HW_REG_XCC_ID, 0, 4)
	v_readlane_b32 s6, v255, 50
	v_readlane_b32 s7, v255, 51
	s_lshl_b32 s4, s4, 6
	s_add_u32 s4, s4, 0x1eb03800
	s_add_u32 s8, s24, s4
	s_addc_u32 s9, s25, 0
	s_add_u32 s10, s24, 0x1eb03c00
	s_addc_u32 s11, s25, 0
	v_mov_b32_e32 v0, 1
	s_waitcnt vmcnt(0) lgkmcnt(0)
	global_atomic_add v1, v65, v0, s[8:9] sc0
	v_readfirstlane_b32 s4, v2
	v_readfirstlane_b32 s5, v3
	s_add_i32 s6, s6, s4
	s_add_i32 s7, s7, s5
	v_writelane_b32 v255, s6, 50
	v_writelane_b32 v255, s7, 51
	s_waitcnt vmcnt(0)
	v_add_u32_e32 v1, 1, v1
	v_cmp_eq_u32_e32 vcc, s6, v1
	s_cbranch_vccz .Lmy_gs_poll_4
	buffer_wbl2 sc1
	s_waitcnt vmcnt(0)
	global_atomic_add v65, v0, s[10:11]

; __device__ __forceinline__ unsigned xb_ld(unsigned* p)              { return __hip_atomic_load(p, __ATOMIC_RELAXED, __HIP_MEMORY_SCOPE_AGENT); }
; __device__ __forceinline__ unsigned xb_add(unsigned* p, unsigned v) { return __hip_atomic_fetch_add(p, v, __ATOMIC_RELAXED, __HIP_MEMORY_SCOPE_AGENT); }
; #define XB_SPIN(cond, bar) do { unsigned _sp = 0; while (cond) { __builtin_amdgcn_s_sleep(1); \
;     if ((++_sp & 255u) == 0u) { if (xb_ld(&(bar)[XB_TMO])) break; if (_sp > XB_SPIN_CAP) { atomicAdd(&(bar)[XB_TMO], 1u); break; } } } } while (0)
; __device__ __forceinline__ void xcd_barrier(const XcdBarrier& b) {
;     asm volatile("s_waitcnt vmcnt(0)" ::: "memory");
;     __syncthreads();
;     if (threadIdx.x == 0) {
;         unsigned* bar = b.bar;
;         __builtin_amdgcn_s_waitcnt(0);
;         unsigned nloc = b.st[0], nx = b.st[1];
;         if (nloc == 0u) { xcd_barrier_complete(bar, b.x, nloc, nx); b.st[0] = nloc; b.st[1] = nx; }
;         const unsigned old = xb_add(&bar[XB_XSUB(b.x)], 1u);
;         const unsigned gen = old / nloc;
;         if (old + 1u == (gen + 1u) * nloc) {
;             __builtin_amdgcn_fence(__ATOMIC_RELEASE, "agent");
;             asm volatile("s_waitcnt vmcnt(0)" ::: "memory");
;             const unsigned og = xb_add(&bar[XB_TOP], 1u);
;             const unsigned tg = og / nx;
;             if (og + 1u == (tg + 1u) * nx) xb_add(&bar[XB_TOPGEN], 1u);
;             else XB_SPIN(xb_ld(&bar[XB_TOPGEN]) == tg, bar);
;             __builtin_amdgcn_fence(__ATOMIC_ACQUIRE, "agent");
;             xb_add(&bar[XB_XGEN(b.x)], 1u);
;             asm volatile("s_waitcnt vmcnt(0)" ::: "memory");
;         } else {
;             XB_SPIN(xb_ld(&bar[XB_XGEN(b.x)]) == gen, bar);
;             __builtin_amdgcn_fence(__ATOMIC_ACQUIRE, "agent");
;             asm volatile("s_waitcnt vmcnt(0)" ::: "memory");
;         }
.LBB0_685:
	s_waitcnt vmcnt(0)
	s_barrier
	s_mov_b64 s[0:1], exec
	v_readlane_b32 s4, v251, 2
	v_readlane_b32 s5, v251, 3
	s_and_b64 s[4:5], s[0:1], s[4:5]
	v_readlane_b32 s40, v253, 26
	s_mov_b64 exec, s[4:5]
	s_cbranch_execz .LBB0_737
	v_mov_b32_e32 v0, 0x26ff0
	ds_read_b64 v[2:3], v0
	s_getreg_b32 s4, hwreg(HW_REG_XCC_ID, 0, 4)
	v_readlane_b32 s6, v255, 50
	v_readlane_b32 s7, v255, 51
	s_lshl_b32 s4, s4, 6
	s_add_u32 s4, s4, 0x1eb03800
	s_add_u32 s8, s24, s4
	s_addc_u32 s9, s25, 0
	s_add_u32 s10, s24, 0x1eb03c00
	s_addc_u32 s11, s25, 0
	v_mov_b32_e32 v0, 1
	s_waitcnt vmcnt(0) lgkmcnt(0)
	global_atomic_add v1, v65, v0, s[8:9] sc0
	v_readfirstlane_b32 s4, v2
	v_readfirstlane_b32 s5, v3
	s_add_i32 s6, s6, s4
	s_add_i32 s7, s7, s5
	v_writelane_b32 v255, s6, 50
	v_writelane_b32 v255, s7, 51
	s_waitcnt vmcnt(0)
	v_add_u32_e32 v1, 1, v1
	v_cmp_eq_u32_e32 vcc, s6, v1
	s_cbranch_vccz .Lmy_gs_poll_5
	buffer_wbl2 sc1
	s_waitcnt vmcnt(0)
	global_atomic_add v65, v0, s[10:11]

; __device__ __forceinline__ unsigned xb_ld(unsigned* p)              { return __hip_atomic_load(p, __ATOMIC_RELAXED, __HIP_MEMORY_SCOPE_AGENT); }
; __device__ __forceinline__ unsigned xb_add(unsigned* p, unsigned v) { return __hip_atomic_fetch_add(p, v, __ATOMIC_RELAXED, __HIP_MEMORY_SCOPE_AGENT); }
; #define XB_SPIN(cond, bar) do { unsigned _sp = 0; while (cond) { __builtin_amdgcn_s_sleep(1); \
;     if ((++_sp & 255u) == 0u) { if (xb_ld(&(bar)[XB_TMO])) break; if (_sp > XB_SPIN_CAP) { atomicAdd(&(bar)[XB_TMO], 1u); break; } } } } while (0)
; __device__ __forceinline__ void xcd_barrier(const XcdBarrier& b) {
;     asm volatile("s_waitcnt vmcnt(0)" ::: "memory");
;     __syncthreads();
;     if (threadIdx.x == 0) {
;         unsigned* bar = b.bar;
;         __builtin_amdgcn_s_waitcnt(0);
;         unsigned nloc = b.st[0], nx = b.st[1];
;         if (nloc == 0u) { xcd_barrier_complete(bar, b.x, nloc, nx); b.st[0] = nloc; b.st[1] = nx; }
;         const unsigned old = xb_add(&bar[XB_XSUB(b.x)], 1u);
;         const unsigned gen = old / nloc;
;         if (old + 1u == (gen + 1u) * nloc) {
;             __builtin_amdgcn_fence(__ATOMIC_RELEASE, "agent");
;             asm volatile("s_waitcnt vmcnt(0)" ::: "memory");
;             const unsigned og = xb_add(&bar[XB_TOP], 1u);
;             const unsigned tg = og / nx;
;             if (og + 1u == (tg + 1u) * nx) xb_add(&bar[XB_TOPGEN], 1u);
;             else XB_SPIN(xb_ld(&bar[XB_TOPGEN]) == tg, bar);
;             __builtin_amdgcn_fence(__ATOMIC_ACQUIRE, "agent");
;             xb_add(&bar[XB_XGEN(b.x)], 1u);
;             asm volatile("s_waitcnt vmcnt(0)" ::: "memory");
;         } else {
;             XB_SPIN(xb_ld(&bar[XB_XGEN(b.x)]) == gen, bar);
;             __builtin_amdgcn_fence(__ATOMIC_ACQUIRE, "agent");
;             asm volatile("s_waitcnt vmcnt(0)" ::: "memory");
;         }
.LBB0_754:
	s_or_b64 exec, exec, s[0:1]
	s_waitcnt vmcnt(0)
	s_waitcnt vmcnt(63) expcnt(7) lgkmcnt(15)
	s_barrier
	s_mov_b64 s[0:1], exec
	v_readlane_b32 s4, v251, 2
	v_readlane_b32 s5, v251, 3
	s_and_b64 s[4:5], s[0:1], s[4:5]
	v_readlane_b32 s40, v254, 53
	s_xor_b64 s[0:1], s[4:5], s[0:1]
	v_readlane_b32 s41, v254, 54
	s_mov_b64 exec, s[4:5]
	s_cbranch_execz .LBB0_807
	v_mov_b32_e32 v0, 0x26ff0
	ds_read_b64 v[2:3], v0
	s_getreg_b32 s4, hwreg(HW_REG_XCC_ID, 0, 4)
	v_readlane_b32 s6, v255, 50
	v_readlane_b32 s7, v255, 51
	s_lshl_b32 s4, s4, 6
	s_add_u32 s4, s4, 0x1eb03800
	s_add_u32 s8, s24, s4
	s_addc_u32 s9, s25, 0
	s_add_u32 s10, s24, 0x1eb03c00
	s_addc_u32 s11, s25, 0
	v_mov_b32_e32 v0, 1
	s_waitcnt vmcnt(0) lgkmcnt(0)
	global_atomic_add v1, v65, v0, s[8:9] sc0
	v_readfirstlane_b32 s4, v2
	v_readfirstlane_b32 s5, v3
	s_add_i32 s6, s6, s4
	s_add_i32 s7, s7, s5
	v_writelane_b32 v255, s6, 50
	v_writelane_b32 v255, s7, 51
	s_waitcnt vmcnt(0)
	v_add_u32_e32 v1, 1, v1
	v_cmp_eq_u32_e32 vcc, s6, v1
	s_cbranch_vccz .Lmy_gs_poll_6
	buffer_wbl2 sc1
	s_waitcnt vmcnt(0)
	global_atomic_add v65, v0, s[10:11]

; __device__ __forceinline__ unsigned xb_ld(unsigned* p)              { return __hip_atomic_load(p, __ATOMIC_RELAXED, __HIP_MEMORY_SCOPE_AGENT); }
; __device__ __forceinline__ unsigned xb_add(unsigned* p, unsigned v) { return __hip_atomic_fetch_add(p, v, __ATOMIC_RELAXED, __HIP_MEMORY_SCOPE_AGENT); }
; #define XB_SPIN(cond, bar) do { unsigned _sp = 0; while (cond) { __builtin_amdgcn_s_sleep(1); \
;     if ((++_sp & 255u) == 0u) { if (xb_ld(&(bar)[XB_TMO])) break; if (_sp > XB_SPIN_CAP) { atomicAdd(&(bar)[XB_TMO], 1u); break; } } } } while (0)
; __device__ __forceinline__ void xcd_barrier(const XcdBarrier& b) {
;     asm volatile("s_waitcnt vmcnt(0)" ::: "memory");
;     __syncthreads();
;     if (threadIdx.x == 0) {
;         unsigned* bar = b.bar;
;         __builtin_amdgcn_s_waitcnt(0);
;         unsigned nloc = b.st[0], nx = b.st[1];
;         if (nloc == 0u) { xcd_barrier_complete(bar, b.x, nloc, nx); b.st[0] = nloc; b.st[1] = nx; }
;         const unsigned old = xb_add(&bar[XB_XSUB(b.x)], 1u);
;         const unsigned gen = old / nloc;
;         if (old + 1u == (gen + 1u) * nloc) {
;             __builtin_amdgcn_fence(__ATOMIC_RELEASE, "agent");
;             asm volatile("s_waitcnt vmcnt(0)" ::: "memory");
;             const unsigned og = xb_add(&bar[XB_TOP], 1u);
;             const unsigned tg = og / nx;
;             if (og + 1u == (tg + 1u) * nx) xb_add(&bar[XB_TOPGEN], 1u);
;             else XB_SPIN(xb_ld(&bar[XB_TOPGEN]) == tg, bar);
;             __builtin_amdgcn_fence(__ATOMIC_ACQUIRE, "agent");
;             xb_add(&bar[XB_XGEN(b.x)], 1u);
;             asm volatile("s_waitcnt vmcnt(0)" ::: "memory");
;         } else {
;             XB_SPIN(xb_ld(&bar[XB_XGEN(b.x)]) == gen, bar);
;             __builtin_amdgcn_fence(__ATOMIC_ACQUIRE, "agent");
;             asm volatile("s_waitcnt vmcnt(0)" ::: "memory");
;         }
.LBB0_832:
	s_waitcnt vmcnt(0)
	s_waitcnt vmcnt(0) lgkmcnt(0)
	s_barrier
	s_mov_b64 s[0:1], exec
	v_readlane_b32 s4, v251, 2
	v_readlane_b32 s5, v251, 3
	v_readlane_b32 s52, v254, 57
	v_readlane_b32 s38, v254, 18
	v_readlane_b32 s42, v254, 49
	v_readlane_b32 s44, v254, 51
	s_and_b64 s[4:5], s[0:1], s[4:5]
	v_readlane_b32 s53, v254, 58
	v_readlane_b32 s39, v254, 19
	v_readlane_b32 s43, v254, 50
	v_readlane_b32 s45, v254, 52
	s_mov_b32 s36, 0x3a800000
	s_mov_b64 exec, s[4:5]
	s_cbranch_execz .LBB0_884
	v_mov_b32_e32 v0, 0x26ff0
	ds_read_b64 v[2:3], v0
	s_getreg_b32 s4, hwreg(HW_REG_XCC_ID, 0, 4)
	v_readlane_b32 s6, v255, 50
	v_readlane_b32 s7, v255, 51
	s_lshl_b32 s4, s4, 6
	s_add_u32 s4, s4, 0x1eb03800
	s_add_u32 s8, s24, s4
	s_addc_u32 s9, s25, 0
	s_add_u32 s10, s24, 0x1eb03c00
	s_addc_u32 s11, s25, 0
	v_mov_b32_e32 v0, 1
	s_waitcnt vmcnt(0) lgkmcnt(0)
	global_atomic_add v1, v65, v0, s[8:9] sc0
	v_readfirstlane_b32 s4, v2
	v_readfirstlane_b32 s5, v3
	s_add_i32 s6, s6, s4
	s_add_i32 s7, s7, s5
	v_writelane_b32 v255, s6, 50
	v_writelane_b32 v255, s7, 51
	s_waitcnt vmcnt(0)
	v_add_u32_e32 v1, 1, v1
	v_cmp_eq_u32_e32 vcc, s6, v1
	s_cbranch_vccz .Lmy_gs_poll_7
	buffer_wbl2 sc1
	s_waitcnt vmcnt(0)
	global_atomic_add v65, v0, s[10:11]

; __device__ __forceinline__ unsigned xb_ld(unsigned* p)              { return __hip_atomic_load(p, __ATOMIC_RELAXED, __HIP_MEMORY_SCOPE_AGENT); }
; __device__ __forceinline__ unsigned xb_add(unsigned* p, unsigned v) { return __hip_atomic_fetch_add(p, v, __ATOMIC_RELAXED, __HIP_MEMORY_SCOPE_AGENT); }
; #define XB_SPIN(cond, bar) do { unsigned _sp = 0; while (cond) { __builtin_amdgcn_s_sleep(1); \
;     if ((++_sp & 255u) == 0u) { if (xb_ld(&(bar)[XB_TMO])) break; if (_sp > XB_SPIN_CAP) { atomicAdd(&(bar)[XB_TMO], 1u); break; } } } } while (0)
; __device__ __forceinline__ void xcd_barrier(const XcdBarrier& b) {
;     asm volatile("s_waitcnt vmcnt(0)" ::: "memory");
;     __syncthreads();
;     if (threadIdx.x == 0) {
;         unsigned* bar = b.bar;
;         __builtin_amdgcn_s_waitcnt(0);
;         unsigned nloc = b.st[0], nx = b.st[1];
;         if (nloc == 0u) { xcd_barrier_complete(bar, b.x, nloc, nx); b.st[0] = nloc; b.st[1] = nx; }
;         const unsigned old = xb_add(&bar[XB_XSUB(b.x)], 1u);
;         const unsigned gen = old / nloc;
;         if (old + 1u == (gen + 1u) * nloc) {
;             __builtin_amdgcn_fence(__ATOMIC_RELEASE, "agent");
;             asm volatile("s_waitcnt vmcnt(0)" ::: "memory");
;             const unsigned og = xb_add(&bar[XB_TOP], 1u);
;             const unsigned tg = og / nx;
;             if (og + 1u == (tg + 1u) * nx) xb_add(&bar[XB_TOPGEN], 1u);
;             else XB_SPIN(xb_ld(&bar[XB_TOPGEN]) == tg, bar);
;             __builtin_amdgcn_fence(__ATOMIC_ACQUIRE, "agent");
;             xb_add(&bar[XB_XGEN(b.x)], 1u);
;             asm volatile("s_waitcnt vmcnt(0)" ::: "memory");
;         } else {
;             XB_SPIN(xb_ld(&bar[XB_XGEN(b.x)]) == gen, bar);
;             __builtin_amdgcn_fence(__ATOMIC_ACQUIRE, "agent");
;             asm volatile("s_waitcnt vmcnt(0)" ::: "memory");
;         }
.LBB0_937:
	s_waitcnt vmcnt(0)
	s_barrier
	s_mov_b64 s[0:1], exec
	v_readlane_b32 s4, v251, 2
	v_readlane_b32 s5, v251, 3
	s_and_b64 s[4:5], s[0:1], s[4:5]
	s_xor_b64 s[0:1], s[4:5], s[0:1]
	s_mov_b64 exec, s[4:5]
	s_cbranch_execz .LBB0_990
	v_mov_b32_e32 v0, 0x26ff0
	ds_read_b64 v[2:3], v0
	s_getreg_b32 s4, hwreg(HW_REG_XCC_ID, 0, 4)
	v_readlane_b32 s6, v255, 50
	v_readlane_b32 s7, v255, 51
	s_lshl_b32 s4, s4, 6
	s_add_u32 s4, s4, 0x1eb03800
	s_add_u32 s8, s24, s4
	s_addc_u32 s9, s25, 0
	s_add_u32 s10, s24, 0x1eb03c00
	s_addc_u32 s11, s25, 0
	v_mov_b32_e32 v0, 1
	s_waitcnt vmcnt(0) lgkmcnt(0)
	global_atomic_add v1, v65, v0, s[8:9] sc0
	v_readfirstlane_b32 s4, v2
	v_readfirstlane_b32 s5, v3
	s_add_i32 s6, s6, s4
	s_add_i32 s7, s7, s5
	v_writelane_b32 v255, s6, 50
	v_writelane_b32 v255, s7, 51
	s_waitcnt vmcnt(0)
	v_add_u32_e32 v1, 1, v1
	v_cmp_eq_u32_e32 vcc, s6, v1
	s_cbranch_vccz .Lmy_gs_poll_8
	buffer_wbl2 sc1
	s_waitcnt vmcnt(0)
	global_atomic_add v65, v0, s[10:11]

; __device__ __forceinline__ unsigned xb_ld(unsigned* p)              { return __hip_atomic_load(p, __ATOMIC_RELAXED, __HIP_MEMORY_SCOPE_AGENT); }
; __device__ __forceinline__ unsigned xb_add(unsigned* p, unsigned v) { return __hip_atomic_fetch_add(p, v, __ATOMIC_RELAXED, __HIP_MEMORY_SCOPE_AGENT); }
; #define XB_SPIN(cond, bar) do { unsigned _sp = 0; while (cond) { __builtin_amdgcn_s_sleep(1); \
;     if ((++_sp & 255u) == 0u) { if (xb_ld(&(bar)[XB_TMO])) break; if (_sp > XB_SPIN_CAP) { atomicAdd(&(bar)[XB_TMO], 1u); break; } } } } while (0)
; __device__ __forceinline__ void xcd_barrier(const XcdBarrier& b) {
;     asm volatile("s_waitcnt vmcnt(0)" ::: "memory");
;     __syncthreads();
;     if (threadIdx.x == 0) {
;         unsigned* bar = b.bar;
;         __builtin_amdgcn_s_waitcnt(0);
;         unsigned nloc = b.st[0], nx = b.st[1];
;         if (nloc == 0u) { xcd_barrier_complete(bar, b.x, nloc, nx); b.st[0] = nloc; b.st[1] = nx; }
;         const unsigned old = xb_add(&bar[XB_XSUB(b.x)], 1u);
;         const unsigned gen = old / nloc;
;         if (old + 1u == (gen + 1u) * nloc) {
;             __builtin_amdgcn_fence(__ATOMIC_RELEASE, "agent");
;             asm volatile("s_waitcnt vmcnt(0)" ::: "memory");
;             const unsigned og = xb_add(&bar[XB_TOP], 1u);
;             const unsigned tg = og / nx;
;             if (og + 1u == (tg + 1u) * nx) xb_add(&bar[XB_TOPGEN], 1u);
;             else XB_SPIN(xb_ld(&bar[XB_TOPGEN]) == tg, bar);
;             __builtin_amdgcn_fence(__ATOMIC_ACQUIRE, "agent");
;             xb_add(&bar[XB_XGEN(b.x)], 1u);
;             asm volatile("s_waitcnt vmcnt(0)" ::: "memory");
;         } else {
;             XB_SPIN(xb_ld(&bar[XB_XGEN(b.x)]) == gen, bar);
;             __builtin_amdgcn_fence(__ATOMIC_ACQUIRE, "agent");
;             asm volatile("s_waitcnt vmcnt(0)" ::: "memory");
;         }
.LBB0_1133:
	s_waitcnt vmcnt(0)
	s_waitcnt vmcnt(0)
	s_barrier
	s_mov_b64 s[0:1], exec
	v_readlane_b32 s4, v251, 2
	v_readlane_b32 s5, v251, 3
	s_and_b64 s[4:5], s[0:1], s[4:5]
	s_xor_b64 s[0:1], s[4:5], s[0:1]
	s_mov_b64 exec, s[4:5]
	s_cbranch_execz .LBB0_1186
	v_mov_b32_e32 v0, 0x26ff0
	ds_read_b64 v[2:3], v0
	s_getreg_b32 s4, hwreg(HW_REG_XCC_ID, 0, 4)
	v_readlane_b32 s6, v255, 50
	v_readlane_b32 s7, v255, 51
	s_lshl_b32 s4, s4, 6
	s_add_u32 s4, s4, 0x1eb03800
	s_add_u32 s8, s24, s4
	s_addc_u32 s9, s25, 0
	s_add_u32 s10, s24, 0x1eb03c00
	s_addc_u32 s11, s25, 0
	v_mov_b32_e32 v0, 1
	s_waitcnt vmcnt(0) lgkmcnt(0)
	global_atomic_add v1, v65, v0, s[8:9] sc0
	v_readfirstlane_b32 s4, v2
	v_readfirstlane_b32 s5, v3
	s_add_i32 s6, s6, s4
	s_add_i32 s7, s7, s5
	v_writelane_b32 v255, s6, 50
	v_writelane_b32 v255, s7, 51
	s_waitcnt vmcnt(0)
	v_add_u32_e32 v1, 1, v1
	v_cmp_eq_u32_e32 vcc, s6, v1
	s_cbranch_vccz .Lmy_gs_poll_11
	buffer_wbl2 sc1
	s_waitcnt vmcnt(0)
	global_atomic_add v65, v0, s[10:11]
